# combined version + accumulator clears as 64 v_mov_b64 before each K-loop
# baseline (speedup 1.0000x reference)
; template <class Epi, class Sched, bool ALIGN_EPI = false, bool SP2 = false>
; __device__ __forceinline__ void gemm_phase(PG8_LAS unsigned char* lds, const Gemm g, const Sched& S, const Epi& E, int wave_s) {
;     ...
;         const bool has_next = S.next(ui + 1, nxt);
;         const char* nA = has_next ? (const char*)g.A + (size_t)nxt.pm * tstepA : cA; const char* nB = has_next ? (const char*)g.Bt + (size_t)nxt.pn * tstepB : cB;
;     ...
; #pragma unroll
;         for (int a = 0; a < 2; ++a)
; #pragma unroll
;             for (int b = 0; b < 2; ++b)
; #pragma unroll
;                 for (int m = 0; m < 4; ++m)
; #pragma unroll
;                     for (int n = 0; n < 2; ++n) acc[a][b][m][n] = (f32x4){0.f, 0.f, 0.f, 0.f};
.LBB0_191:
	s_ashr_i32 s23, s22, 31
	s_lshl_b64 s[24:25], s[22:23], 20
	s_add_u32 s24, s2, s24
	s_addc_u32 s25, s30, s25
	s_and_b64 s[36:37], s[34:35], exec
	s_cselect_b32 s23, s25, s27
	s_cselect_b32 s39, s24, s26
	s_ashr_i32 s21, s20, 31
	s_lshl_b64 s[36:37], s[20:21], 20
	s_add_u32 s40, s42, s36
	s_addc_u32 s41, s43, s37
	s_and_b64 s[36:37], s[34:35], exec
	s_cselect_b32 s21, s41, s19
	s_cselect_b32 s52, s40, s18
	s_add_u32 s53, s18, 0x100
	s_addc_u32 s54, s19, 0
	s_add_u32 s18, s26, 0x80080
	s_addc_u32 s19, s27, 0
	s_mov_b32 s55, -2
	s_waitcnt vmcnt(0) lgkmcnt(0)
	v_mov_b64_e32 v[4:5], 0
	v_mov_b64_e32 v[6:7], 0
	v_mov_b64_e32 v[8:9], 0
	v_mov_b64_e32 v[10:11], 0
	v_mov_b64_e32 v[12:13], 0
	v_mov_b64_e32 v[14:15], 0
	v_mov_b64_e32 v[16:17], 0
	v_mov_b64_e32 v[18:19], 0
	v_mov_b64_e32 v[20:21], 0
	v_mov_b64_e32 v[22:23], 0
	v_mov_b64_e32 v[24:25], 0
	v_mov_b64_e32 v[26:27], 0
	v_mov_b64_e32 v[28:29], 0
	v_mov_b64_e32 v[30:31], 0
	v_mov_b64_e32 v[32:33], 0
	v_mov_b64_e32 v[34:35], 0
	v_mov_b64_e32 v[36:37], 0
	v_mov_b64_e32 v[38:39], 0
	v_mov_b64_e32 v[40:41], 0
	v_mov_b64_e32 v[42:43], 0
	v_mov_b64_e32 v[44:45], 0
	v_mov_b64_e32 v[46:47], 0
	v_mov_b64_e32 v[48:49], 0
	v_mov_b64_e32 v[50:51], 0
	v_mov_b64_e32 v[52:53], 0
	v_mov_b64_e32 v[54:55], 0
	v_mov_b64_e32 v[56:57], 0
	v_mov_b64_e32 v[58:59], 0
	v_mov_b64_e32 v[60:61], 0
	v_mov_b64_e32 v[62:63], 0
	v_mov_b64_e32 v[64:65], 0
	v_mov_b64_e32 v[66:67], 0
	v_mov_b64_e32 v[68:69], 0
	v_mov_b64_e32 v[70:71], 0
	v_mov_b64_e32 v[72:73], 0
	v_mov_b64_e32 v[74:75], 0
	v_mov_b64_e32 v[76:77], 0
	v_mov_b64_e32 v[78:79], 0
	v_mov_b64_e32 v[80:81], 0
	v_mov_b64_e32 v[82:83], 0
	v_mov_b64_e32 v[84:85], 0
	v_mov_b64_e32 v[86:87], 0
	v_mov_b64_e32 v[88:89], 0
	v_mov_b64_e32 v[90:91], 0
	v_mov_b64_e32 v[92:93], 0
	v_mov_b64_e32 v[94:95], 0
	v_mov_b64_e32 v[96:97], 0
	v_mov_b64_e32 v[98:99], 0
	v_mov_b64_e32 v[100:101], 0
	v_mov_b64_e32 v[102:103], 0
	v_mov_b64_e32 v[104:105], 0
	v_mov_b64_e32 v[106:107], 0
	v_mov_b64_e32 v[108:109], 0
	v_mov_b64_e32 v[110:111], 0
	v_mov_b64_e32 v[112:113], 0
	v_mov_b64_e32 v[114:115], 0
	v_mov_b64_e32 v[116:117], 0
	v_mov_b64_e32 v[118:119], 0
	v_mov_b64_e32 v[120:121], 0
	v_mov_b64_e32 v[122:123], 0
	v_mov_b64_e32 v[124:125], 0
	v_mov_b64_e32 v[126:127], 0
	v_mov_b64_e32 v[128:129], 0
	v_mov_b64_e32 v[130:131], 0
	v_add_u32_e32 v255, 0x10000, v149

; template <class Epi, class Sched, bool ALIGN_EPI = false, bool SP2 = false>
; __device__ __forceinline__ void gemm_phase(PG8_LAS unsigned char* lds, const Gemm g, const Sched& S, const Epi& E, int wave_s) {
;     ...
;         const bool has_next = S.next(ui + 1, nxt);
;         const char* nA = has_next ? (const char*)g.A + (size_t)nxt.pm * tstepA : cA; const char* nB = has_next ? (const char*)g.Bt + (size_t)nxt.pn * tstepB : cB;
;     ...
; #pragma unroll
;         for (int a = 0; a < 2; ++a)
; #pragma unroll
;             for (int b = 0; b < 2; ++b)
; #pragma unroll
;                 for (int m = 0; m < 4; ++m)
; #pragma unroll
;                     for (int n = 0; n < 2; ++n) acc[a][b][m][n] = (f32x4){0.f, 0.f, 0.f, 0.f};
.LBB0_567:
	s_ashr_i32 s19, s18, 31
	s_lshl_b64 s[22:23], s[18:19], 18
	s_add_u32 s22, s46, s22
	s_addc_u32 s23, s47, s23
	s_and_b64 s[38:39], s[38:39], exec
	s_cselect_b32 s19, s23, s27
	s_cselect_b32 s58, s22, s26
	s_add_u32 s59, s26, 0x100
	s_addc_u32 s66, s27, 0
	s_mov_b32 s67, -2
	s_waitcnt vmcnt(0) lgkmcnt(0)
	v_mov_b64_e32 v[4:5], 0
	v_mov_b64_e32 v[6:7], 0
	v_mov_b64_e32 v[8:9], 0
	v_mov_b64_e32 v[10:11], 0
	v_mov_b64_e32 v[12:13], 0
	v_mov_b64_e32 v[14:15], 0
	v_mov_b64_e32 v[16:17], 0
	v_mov_b64_e32 v[18:19], 0
	v_mov_b64_e32 v[20:21], 0
	v_mov_b64_e32 v[22:23], 0
	v_mov_b64_e32 v[24:25], 0
	v_mov_b64_e32 v[26:27], 0
	v_mov_b64_e32 v[28:29], 0
	v_mov_b64_e32 v[30:31], 0
	v_mov_b64_e32 v[32:33], 0
	v_mov_b64_e32 v[34:35], 0
	v_mov_b64_e32 v[36:37], 0
	v_mov_b64_e32 v[38:39], 0
	v_mov_b64_e32 v[40:41], 0
	v_mov_b64_e32 v[42:43], 0
	v_mov_b64_e32 v[44:45], 0
	v_mov_b64_e32 v[46:47], 0
	v_mov_b64_e32 v[48:49], 0
	v_mov_b64_e32 v[50:51], 0
	v_mov_b64_e32 v[52:53], 0
	v_mov_b64_e32 v[54:55], 0
	v_mov_b64_e32 v[56:57], 0
	v_mov_b64_e32 v[58:59], 0
	v_mov_b64_e32 v[60:61], 0
	v_mov_b64_e32 v[62:63], 0
	v_mov_b64_e32 v[64:65], 0
	v_mov_b64_e32 v[66:67], 0
	v_mov_b64_e32 v[68:69], 0
	v_mov_b64_e32 v[70:71], 0
	v_mov_b64_e32 v[72:73], 0
	v_mov_b64_e32 v[74:75], 0
	v_mov_b64_e32 v[76:77], 0
	v_mov_b64_e32 v[78:79], 0
	v_mov_b64_e32 v[80:81], 0
	v_mov_b64_e32 v[82:83], 0
	v_mov_b64_e32 v[84:85], 0
	v_mov_b64_e32 v[86:87], 0
	v_mov_b64_e32 v[88:89], 0
	v_mov_b64_e32 v[90:91], 0
	v_mov_b64_e32 v[92:93], 0
	v_mov_b64_e32 v[94:95], 0
	v_mov_b64_e32 v[96:97], 0
	v_mov_b64_e32 v[98:99], 0
	v_mov_b64_e32 v[100:101], 0
	v_mov_b64_e32 v[102:103], 0
	v_mov_b64_e32 v[104:105], 0
	v_mov_b64_e32 v[106:107], 0
	v_mov_b64_e32 v[108:109], 0
	v_mov_b64_e32 v[110:111], 0
	v_mov_b64_e32 v[112:113], 0
	v_mov_b64_e32 v[114:115], 0
	v_mov_b64_e32 v[116:117], 0
	v_mov_b64_e32 v[118:119], 0
	v_mov_b64_e32 v[120:121], 0
	v_mov_b64_e32 v[122:123], 0
	v_mov_b64_e32 v[124:125], 0
	v_mov_b64_e32 v[126:127], 0
	v_mov_b64_e32 v[128:129], 0
	v_mov_b64_e32 v[130:131], 0
	v_add_u32_e32 v255, 0x10000, v186

; template <class Epi, class Sched, bool ALIGN_EPI = false, bool SP2 = false>
; __device__ __forceinline__ void gemm_phase(PG8_LAS unsigned char* lds, const Gemm g, const Sched& S, const Epi& E, int wave_s) {
;     ...
;         const bool has_next = S.next(ui + 1, nxt);
;         const char* nA = has_next ? (const char*)g.A + (size_t)nxt.pm * tstepA : cA; const char* nB = has_next ? (const char*)g.Bt + (size_t)nxt.pn * tstepB : cB;
;     ...
; #pragma unroll
;         for (int a = 0; a < 2; ++a)
; #pragma unroll
;             for (int b = 0; b < 2; ++b)
; #pragma unroll
;                 for (int m = 0; m < 4; ++m)
; #pragma unroll
;                     for (int n = 0; n < 2; ++n) acc[a][b][m][n] = (f32x4){0.f, 0.f, 0.f, 0.f};
.LBB0_589:
	s_ashr_i32 s47, s46, 31
	s_lshl_b64 s[0:1], s[46:47], 21
	s_add_u32 s50, s22, s0
	s_addc_u32 s51, s23, s1
	s_and_b64 s[0:1], s[38:39], exec
	s_cselect_b32 s38, s51, s7
	s_cselect_b32 s39, s50, s6
	s_add_u32 s47, s6, 0x100
	s_addc_u32 s56, s7, 0
	s_mov_b32 s57, -2
	s_waitcnt vmcnt(0) lgkmcnt(0)
	v_mov_b64_e32 v[4:5], 0
	v_mov_b64_e32 v[6:7], 0
	v_mov_b64_e32 v[8:9], 0
	v_mov_b64_e32 v[10:11], 0
	v_mov_b64_e32 v[12:13], 0
	v_mov_b64_e32 v[14:15], 0
	v_mov_b64_e32 v[16:17], 0
	v_mov_b64_e32 v[18:19], 0
	v_mov_b64_e32 v[20:21], 0
	v_mov_b64_e32 v[22:23], 0
	v_mov_b64_e32 v[24:25], 0
	v_mov_b64_e32 v[26:27], 0
	v_mov_b64_e32 v[28:29], 0
	v_mov_b64_e32 v[30:31], 0
	v_mov_b64_e32 v[32:33], 0
	v_mov_b64_e32 v[34:35], 0
	v_mov_b64_e32 v[36:37], 0
	v_mov_b64_e32 v[38:39], 0
	v_mov_b64_e32 v[40:41], 0
	v_mov_b64_e32 v[42:43], 0
	v_mov_b64_e32 v[44:45], 0
	v_mov_b64_e32 v[46:47], 0
	v_mov_b64_e32 v[48:49], 0
	v_mov_b64_e32 v[50:51], 0
	v_mov_b64_e32 v[52:53], 0
	v_mov_b64_e32 v[54:55], 0
	v_mov_b64_e32 v[56:57], 0
	v_mov_b64_e32 v[58:59], 0
	v_mov_b64_e32 v[60:61], 0
	v_mov_b64_e32 v[62:63], 0
	v_mov_b64_e32 v[64:65], 0
	v_mov_b64_e32 v[66:67], 0
	v_mov_b64_e32 v[68:69], 0
	v_mov_b64_e32 v[70:71], 0
	v_mov_b64_e32 v[72:73], 0
	v_mov_b64_e32 v[74:75], 0
	v_mov_b64_e32 v[76:77], 0
	v_mov_b64_e32 v[78:79], 0
	v_mov_b64_e32 v[80:81], 0
	v_mov_b64_e32 v[82:83], 0
	v_mov_b64_e32 v[84:85], 0
	v_mov_b64_e32 v[86:87], 0
	v_mov_b64_e32 v[88:89], 0
	v_mov_b64_e32 v[90:91], 0
	v_mov_b64_e32 v[92:93], 0
	v_mov_b64_e32 v[94:95], 0
	v_mov_b64_e32 v[96:97], 0
	v_mov_b64_e32 v[98:99], 0
	v_mov_b64_e32 v[104:105], 0
	v_mov_b64_e32 v[106:107], 0
	v_mov_b64_e32 v[108:109], 0
	v_mov_b64_e32 v[110:111], 0
	v_mov_b64_e32 v[112:113], 0
	v_mov_b64_e32 v[114:115], 0
	v_mov_b64_e32 v[116:117], 0
	v_mov_b64_e32 v[118:119], 0
	v_mov_b64_e32 v[128:129], 0
	v_mov_b64_e32 v[130:131], 0
	v_mov_b64_e32 v[132:133], 0
	v_mov_b64_e32 v[134:135], 0
	v_mov_b64_e32 v[136:137], 0
	v_mov_b64_e32 v[138:139], 0
	v_mov_b64_e32 v[140:141], 0
	v_mov_b64_e32 v[142:143], 0
	v_add_u32_e32 v255, 0x10000, v194

; template <class Epi, class Sched, bool ALIGN_EPI = false, bool SP2 = false>
; __device__ __forceinline__ void gemm_phase(PG8_LAS unsigned char* lds, const Gemm g, const Sched& S, const Epi& E, int wave_s) {
;     ...
;         const bool has_next = S.next(ui + 1, nxt);
;         const char* nA = has_next ? (const char*)g.A + (size_t)nxt.pm * tstepA : cA; const char* nB = has_next ? (const char*)g.Bt + (size_t)nxt.pn * tstepB : cB;
;     ...
; #pragma unroll
;         for (int a = 0; a < 2; ++a)
; #pragma unroll
;             for (int b = 0; b < 2; ++b)
; #pragma unroll
;                 for (int m = 0; m < 4; ++m)
; #pragma unroll
;                     for (int n = 0; n < 2; ++n) acc[a][b][m][n] = (f32x4){0.f, 0.f, 0.f, 0.f};
.LBB0_660:
	s_ashr_i32 s7, s6, 31
	s_lshl_b64 s[16:17], s[6:7], 20
	s_add_u32 s22, s2, s16
	s_addc_u32 s23, s30, s17
	s_and_b64 s[16:17], s[36:37], exec
	s_cselect_b32 s7, s23, s27
	s_cselect_b32 s57, s22, s26
	s_ashr_i32 s5, s4, 31
	s_lshl_b64 s[16:17], s[4:5], 20
	s_add_u32 s16, s44, s16
	s_addc_u32 s17, s45, s17
	s_and_b64 s[42:43], s[36:37], exec
	s_cselect_b32 s5, s17, s19
	s_cselect_b32 s58, s16, s18
	s_add_u32 s59, s18, 0x100
	s_addc_u32 s66, s19, 0
	s_add_u32 s18, s26, 0x80080
	s_addc_u32 s19, s27, 0
	s_mov_b32 s67, -2
	v_mov_b64_e32 v[4:5], 0
	v_mov_b64_e32 v[6:7], 0
	v_mov_b64_e32 v[8:9], 0
	v_mov_b64_e32 v[10:11], 0
	v_mov_b64_e32 v[12:13], 0
	v_mov_b64_e32 v[14:15], 0
	v_mov_b64_e32 v[16:17], 0
	v_mov_b64_e32 v[18:19], 0
	v_mov_b64_e32 v[20:21], 0
	v_mov_b64_e32 v[22:23], 0
	v_mov_b64_e32 v[24:25], 0
	v_mov_b64_e32 v[26:27], 0
	v_mov_b64_e32 v[28:29], 0
	v_mov_b64_e32 v[30:31], 0
	v_mov_b64_e32 v[32:33], 0
	v_mov_b64_e32 v[34:35], 0
	v_mov_b64_e32 v[36:37], 0
	v_mov_b64_e32 v[38:39], 0
	v_mov_b64_e32 v[40:41], 0
	v_mov_b64_e32 v[42:43], 0
	v_mov_b64_e32 v[44:45], 0
	v_mov_b64_e32 v[46:47], 0
	v_mov_b64_e32 v[48:49], 0
	v_mov_b64_e32 v[50:51], 0
	v_mov_b64_e32 v[52:53], 0
	v_mov_b64_e32 v[54:55], 0
	v_mov_b64_e32 v[56:57], 0
	v_mov_b64_e32 v[58:59], 0
	v_mov_b64_e32 v[60:61], 0
	v_mov_b64_e32 v[62:63], 0
	v_mov_b64_e32 v[64:65], 0
	v_mov_b64_e32 v[66:67], 0
	v_mov_b64_e32 v[68:69], 0
	v_mov_b64_e32 v[70:71], 0
	v_mov_b64_e32 v[72:73], 0
	v_mov_b64_e32 v[74:75], 0
	v_mov_b64_e32 v[76:77], 0
	v_mov_b64_e32 v[78:79], 0
	v_mov_b64_e32 v[80:81], 0
	v_mov_b64_e32 v[82:83], 0
	v_mov_b64_e32 v[84:85], 0
	v_mov_b64_e32 v[86:87], 0
	v_mov_b64_e32 v[88:89], 0
	v_mov_b64_e32 v[90:91], 0
	v_mov_b64_e32 v[92:93], 0
	v_mov_b64_e32 v[94:95], 0
	v_mov_b64_e32 v[96:97], 0
	v_mov_b64_e32 v[98:99], 0
	v_mov_b64_e32 v[100:101], 0
	v_mov_b64_e32 v[102:103], 0
	v_mov_b64_e32 v[104:105], 0
	v_mov_b64_e32 v[106:107], 0
	v_mov_b64_e32 v[124:125], 0
	v_mov_b64_e32 v[126:127], 0
	v_mov_b64_e32 v[128:129], 0
	v_mov_b64_e32 v[130:131], 0
	v_mov_b64_e32 v[132:133], 0
	v_mov_b64_e32 v[134:135], 0
	v_mov_b64_e32 v[136:137], 0
	v_mov_b64_e32 v[138:139], 0
	v_mov_b64_e32 v[140:141], 0
	v_mov_b64_e32 v[142:143], 0
	v_mov_b64_e32 v[144:145], 0
	v_mov_b64_e32 v[146:147], 0
	v_add_u32_e32 v255, 0x10000, v211

; template <class Epi, class Sched, bool ALIGN_EPI = false, bool SP2 = false>
; __device__ __forceinline__ void gemm_phase(PG8_LAS unsigned char* lds, const Gemm g, const Sched& S, const Epi& E, int wave_s) {
;     ...
;         const bool has_next = S.next(ui + 1, nxt);
;         const char* nA = has_next ? (const char*)g.A + (size_t)nxt.pm * tstepA : cA; const char* nB = has_next ? (const char*)g.Bt + (size_t)nxt.pn * tstepB : cB;
;     ...
; #pragma unroll
;         for (int a = 0; a < 2; ++a)
; #pragma unroll
;             for (int b = 0; b < 2; ++b)
; #pragma unroll
;                 for (int m = 0; m < 4; ++m)
; #pragma unroll
;                     for (int n = 0; n < 2; ++n) acc[a][b][m][n] = (f32x4){0.f, 0.f, 0.f, 0.f};
.LBB0_789:
	s_ashr_i32 s21, s20, 31
	s_lshl_b64 s[22:23], s[20:21], 20
	s_add_u32 s22, s2, s22
	s_addc_u32 s23, s30, s23
	s_and_b64 s[24:25], s[36:37], exec
	s_cselect_b32 s21, s23, s27
	s_cselect_b32 s51, s22, s26
	s_ashr_i32 s17, s16, 31
	s_lshl_b64 s[24:25], s[16:17], 20
	s_add_u32 s24, s40, s24
	s_addc_u32 s25, s41, s25
	s_and_b64 s[38:39], s[36:37], exec
	s_cselect_b32 s17, s25, s19
	s_cselect_b32 s52, s24, s18
	s_add_u32 s53, s18, 0x100
	s_addc_u32 s54, s19, 0
	s_add_u32 s18, s26, 0x80080
	s_addc_u32 s19, s27, 0
	s_mov_b32 s55, -2
	s_waitcnt lgkmcnt(0)
	v_mov_b64_e32 v[4:5], 0
	v_mov_b64_e32 v[6:7], 0
	v_mov_b64_e32 v[8:9], 0
	v_mov_b64_e32 v[10:11], 0
	v_mov_b64_e32 v[12:13], 0
	v_mov_b64_e32 v[14:15], 0
	v_mov_b64_e32 v[16:17], 0
	v_mov_b64_e32 v[18:19], 0
	v_mov_b64_e32 v[20:21], 0
	v_mov_b64_e32 v[22:23], 0
	v_mov_b64_e32 v[24:25], 0
	v_mov_b64_e32 v[26:27], 0
	v_mov_b64_e32 v[28:29], 0
	v_mov_b64_e32 v[30:31], 0
	v_mov_b64_e32 v[32:33], 0
	v_mov_b64_e32 v[34:35], 0
	v_mov_b64_e32 v[36:37], 0
	v_mov_b64_e32 v[38:39], 0
	v_mov_b64_e32 v[40:41], 0
	v_mov_b64_e32 v[42:43], 0
	v_mov_b64_e32 v[44:45], 0
	v_mov_b64_e32 v[46:47], 0
	v_mov_b64_e32 v[48:49], 0
	v_mov_b64_e32 v[50:51], 0
	v_mov_b64_e32 v[52:53], 0
	v_mov_b64_e32 v[54:55], 0
	v_mov_b64_e32 v[56:57], 0
	v_mov_b64_e32 v[58:59], 0
	v_mov_b64_e32 v[60:61], 0
	v_mov_b64_e32 v[62:63], 0
	v_mov_b64_e32 v[64:65], 0
	v_mov_b64_e32 v[66:67], 0
	v_mov_b64_e32 v[68:69], 0
	v_mov_b64_e32 v[70:71], 0
	v_mov_b64_e32 v[72:73], 0
	v_mov_b64_e32 v[74:75], 0
	v_mov_b64_e32 v[76:77], 0
	v_mov_b64_e32 v[78:79], 0
	v_mov_b64_e32 v[80:81], 0
	v_mov_b64_e32 v[82:83], 0
	v_mov_b64_e32 v[84:85], 0
	v_mov_b64_e32 v[86:87], 0
	v_mov_b64_e32 v[88:89], 0
	v_mov_b64_e32 v[90:91], 0
	v_mov_b64_e32 v[92:93], 0
	v_mov_b64_e32 v[94:95], 0
	v_mov_b64_e32 v[96:97], 0
	v_mov_b64_e32 v[98:99], 0
	v_mov_b64_e32 v[100:101], 0
	v_mov_b64_e32 v[102:103], 0
	v_mov_b64_e32 v[104:105], 0
	v_mov_b64_e32 v[106:107], 0
	v_mov_b64_e32 v[108:109], 0
	v_mov_b64_e32 v[110:111], 0
	v_mov_b64_e32 v[112:113], 0
	v_mov_b64_e32 v[114:115], 0
	v_mov_b64_e32 v[116:117], 0
	v_mov_b64_e32 v[118:119], 0
	v_mov_b64_e32 v[120:121], 0
	v_mov_b64_e32 v[122:123], 0
	v_mov_b64_e32 v[124:125], 0
	v_mov_b64_e32 v[126:127], 0
	v_mov_b64_e32 v[128:129], 0
	v_mov_b64_e32 v[130:131], 0
	v_add_u32_e32 v255, 0x10000, v143

; template <class Epi, class Sched, bool ALIGN_EPI = false, bool SP2 = false>
; __device__ __forceinline__ void gemm_phase(PG8_LAS unsigned char* lds, const Gemm g, const Sched& S, const Epi& E, int wave_s) {
;     ...
; #pragma unroll
;         for (int a = 0; a < 2; ++a)
; #pragma unroll
;             for (int b = 0; b < 2; ++b)
; #pragma unroll
;                 for (int m = 0; m < 4; ++m)
; #pragma unroll
;                     for (int n = 0; n < 2; ++n) acc[a][b][m][n] = (f32x4){0.f, 0.f, 0.f, 0.f};
.LBB0_862:
	s_add_u32 s36, s22, 0x100
	s_addc_u32 s37, s23, 0
	s_mov_b32 s53, -2
	s_waitcnt vmcnt(0) lgkmcnt(0)
	v_mov_b64_e32 v[4:5], 0
	v_mov_b64_e32 v[6:7], 0
	v_mov_b64_e32 v[8:9], 0
	v_mov_b64_e32 v[10:11], 0
	v_mov_b64_e32 v[12:13], 0
	v_mov_b64_e32 v[14:15], 0
	v_mov_b64_e32 v[16:17], 0
	v_mov_b64_e32 v[18:19], 0
	v_mov_b64_e32 v[20:21], 0
	v_mov_b64_e32 v[22:23], 0
	v_mov_b64_e32 v[24:25], 0
	v_mov_b64_e32 v[26:27], 0
	v_mov_b64_e32 v[28:29], 0
	v_mov_b64_e32 v[30:31], 0
	v_mov_b64_e32 v[32:33], 0
	v_mov_b64_e32 v[34:35], 0
	v_mov_b64_e32 v[36:37], 0
	v_mov_b64_e32 v[38:39], 0
	v_mov_b64_e32 v[40:41], 0
	v_mov_b64_e32 v[42:43], 0
	v_mov_b64_e32 v[44:45], 0
	v_mov_b64_e32 v[46:47], 0
	v_mov_b64_e32 v[48:49], 0
	v_mov_b64_e32 v[50:51], 0
	v_mov_b64_e32 v[52:53], 0
	v_mov_b64_e32 v[54:55], 0
	v_mov_b64_e32 v[56:57], 0
	v_mov_b64_e32 v[58:59], 0
	v_mov_b64_e32 v[60:61], 0
	v_mov_b64_e32 v[62:63], 0
	v_mov_b64_e32 v[64:65], 0
	v_mov_b64_e32 v[66:67], 0
	v_mov_b64_e32 v[68:69], 0
	v_mov_b64_e32 v[70:71], 0
	v_mov_b64_e32 v[72:73], 0
	v_mov_b64_e32 v[74:75], 0
	v_mov_b64_e32 v[76:77], 0
	v_mov_b64_e32 v[78:79], 0
	v_mov_b64_e32 v[80:81], 0
	v_mov_b64_e32 v[82:83], 0
	v_mov_b64_e32 v[84:85], 0
	v_mov_b64_e32 v[86:87], 0
	v_mov_b64_e32 v[88:89], 0
	v_mov_b64_e32 v[90:91], 0
	v_mov_b64_e32 v[92:93], 0
	v_mov_b64_e32 v[94:95], 0
	v_mov_b64_e32 v[96:97], 0
	v_mov_b64_e32 v[98:99], 0
	v_mov_b64_e32 v[100:101], 0
	v_mov_b64_e32 v[102:103], 0
	v_mov_b64_e32 v[104:105], 0
	v_mov_b64_e32 v[106:107], 0
	v_mov_b64_e32 v[108:109], 0
	v_mov_b64_e32 v[110:111], 0
	v_mov_b64_e32 v[112:113], 0
	v_mov_b64_e32 v[114:115], 0
	v_mov_b64_e32 v[116:117], 0
	v_mov_b64_e32 v[118:119], 0
	v_mov_b64_e32 v[120:121], 0
	v_mov_b64_e32 v[122:123], 0
	v_mov_b64_e32 v[124:125], 0
	v_mov_b64_e32 v[126:127], 0
	v_mov_b64_e32 v[128:129], 0
	v_mov_b64_e32 v[130:131], 0
	v_add_u32_e32 v255, 0x10000, v184
